# v39 + FoX unit prologue: the four Q fragments staged HBM->LDS directly with global_load_lds_dwordx4 (lane-linear stage image; M0 compensates the doubled inst offset) instead of VGPR loads + ds_write_b
# baseline (speedup 1.0000x reference)
.LBB0_302:
	s_add_i32 s54, s56, s70
	v_or_b32_e32 v64, s54, v136
	v_ashrrev_i32_e32 v65, 31, v64
	v_lshl_add_u64 v[0:1], s[72:73], 0, v[64:65]
	v_lshlrev_b64 v[0:1], 7, v[0:1]
	v_lshl_add_u64 v[4:5], v[110:111], 0, v[0:1]
	v_readfirstlane_b32 s100, v189
	s_add_i32 m0, s100, 0xec00
	s_nop 0
	global_load_lds_dwordx4 v[4:5], off
	s_add_i32 m0, s100, 0xefe0
	s_nop 0
	global_load_lds_dwordx4 v[4:5], off offset:32
	s_add_i32 m0, s100, 0xf3c0
	s_nop 0
	global_load_lds_dwordx4 v[4:5], off offset:64
	s_add_i32 m0, s100, 0xf7a0
	s_nop 0
	global_load_lds_dwordx4 v[4:5], off offset:96
	s_add_i32 s4, s56, 0x100
	s_lshr_b32 s55, s4, 6
	s_add_i32 s16, s55, -1
	s_ashr_i32 s4, s54, 6
	s_lshl_b32 s64, s16, 6
	s_sub_i32 s17, s16, s4
	s_lshl_b64 s[4:5], s[64:65], 7
	v_lshl_add_u64 v[8:9], v[132:133], 0, s[4:5]
	global_load_dwordx4 v[8:11], v[8:9], off
	s_lshl_b32 s48, s56, 7
	s_mov_b32 s49, s65
	s_mov_b32 s57, 0
	s_cmp_lt_i32 s17, 2
	v_lshl_add_u64 v[24:25], v[130:131], 0, s[4:5]
	global_load_dwordx4 v[24:27], v[24:25], off
	v_lshl_add_u64 v[4:5], v[130:131], 0, s[48:49]
	v_add_co_u32_e32 v4, vcc, s11, v4
	v_lshl_add_u32 v28, v64, 2, 0
	s_nop 1
	v_addc_co_u32_e32 v5, vcc, 0, v5, vcc
	global_load_dwordx4 v[4:7], v[4:5], off
	ds_read_b32 v190, v28 offset:49920
	s_waitcnt vmcnt(1)
	ds_write_b128 v109, v[24:27] offset:33280
	s_waitcnt vmcnt(0)
	ds_write_b128 v109, v[4:7] offset:8320
	ds_write_b128 v142, v[8:11] offset:16640
	s_waitcnt lgkmcnt(0)
	s_barrier
	s_cbranch_scc1 .LBB0_314
	s_add_i32 s62, s17, -1
	s_add_i32 s4, s56, 64
	s_mov_b32 s63, 0
